# attention main loops: waves 4-7 hold priority 2 from the rendezvous through the first four PV MFMAs (waves 0-3 stay at 1) to balance the two wave groups
# speedup vs baseline: 1.0053x; 1.0053x over previous
.Lstg_x_3:
	v_exp_f32_e32 v227, v56
	v_exp_f32_e32 v228, v57
	v_exp_f32_e32 v229, v58
	v_exp_f32_e32 v230, v59
	v_exp_f32_e32 v231, v60
	v_exp_f32_e32 v232, v61
	v_exp_f32_e32 v233, v62
	v_exp_f32_e32 v234, v63
	v_cvt_pk_bf16_f32 v48, v64, v65
	v_cvt_pk_bf16_f32 v49, v66, v67
	v_cvt_pk_bf16_f32 v50, v68, v69
	v_cvt_pk_bf16_f32 v51, v70, v71
	v_cvt_pk_bf16_f32 v52, v72, v73
	v_cvt_pk_bf16_f32 v53, v74, v75
	v_cvt_pk_bf16_f32 v54, v76, v77
	v_cvt_pk_bf16_f32 v55, v78, v79
	v_cvt_pk_bf16_f32 v56, v219, v220
	v_cvt_pk_bf16_f32 v57, v221, v222
	v_cvt_pk_bf16_f32 v58, v223, v224
	v_cvt_pk_bf16_f32 v59, v225, v226
	v_cvt_pk_bf16_f32 v60, v227, v228
	v_cvt_pk_bf16_f32 v61, v229, v230
	v_cvt_pk_bf16_f32 v62, v231, v232
	v_cvt_pk_bf16_f32 v63, v233, v234
	s_setprio 2
	s_cmp_lg_u32 s98, 0
	s_cbranch_scc1 .Lstg_y_4
	s_setprio 1
	s_waitcnt lgkmcnt(0)
	s_barrier
.Lstg_y_4:
	s_mul_i32 s9, s77, 0x2400
	v_add_u32_e32 v235, s9, v199
	ds_read_b128 v[160:163], v235
	ds_read_b128 v[156:159], v235 offset:32
	ds_read_b128 v[164:167], v235 offset:4608
	ds_read_b128 v[152:155], v235 offset:4640
	ds_read_b128 v[144:147], v235 offset:64
	ds_read_b128 v[140:143], v235 offset:96
	ds_read_b128 v[148:151], v235 offset:4672
	ds_read_b128 v[136:139], v235 offset:4704
	s_waitcnt lgkmcnt(14)
	v_mfma_f32_32x32x16_bf16 v[16:31], v[128:131], v[48:51], v[16:31]
	v_add_f32_e32 v64, v64, v219
	v_add_f32_e32 v65, v65, v220
	v_add_f32_e32 v66, v66, v221
	v_add_f32_e32 v67, v67, v222
	v_add_f32_e32 v68, v68, v223
	s_mul_i32 s9, s8, 0x2400
	s_cmp_eq_u32 s33, 1
	s_cselect_b32 s18, 0, 0x2400
	s_add_i32 s76, s76, 1
	v_lshl_add_u64 v[190:191], v[190:191], 0, s[20:21]
	v_lshl_add_u64 v[192:193], v[192:193], 0, s[22:23]
	s_cmp_eq_u32 s76, 31
	s_waitcnt lgkmcnt(13)
	v_mfma_f32_32x32x16_bf16 v[0:15], v[132:135], v[48:51], v[0:15]
	v_add_f32_e32 v69, v69, v224
	v_add_f32_e32 v70, v70, v225
	v_add_f32_e32 v71, v71, v226
	v_add_f32_e32 v72, v72, v227
	v_add_f32_e32 v73, v73, v228
	v_add_u32_e32 v48, s9, v177
	s_waitcnt vmcnt(1)
	ds_write_b128 v48, v[104:107]
	v_add_u32_e32 v48, s18, v198
	v_add_u32_e32 v48, 0x4800, v48
	s_waitcnt vmcnt(0)
	ds_write2_b64 v48, v[96:97], v[98:99] offset1:2
	v_mfma_f32_32x32x16_bf16 v[16:31], v[116:119], v[52:55], v[16:31]
	v_add_f32_e32 v74, v74, v229
	v_add_f32_e32 v75, v75, v230
	v_add_f32_e32 v76, v76, v231
	v_add_f32_e32 v77, v77, v232
	v_add_f32_e32 v78, v78, v233
	s_waitcnt lgkmcnt(14)
	v_mfma_f32_32x32x16_bf16 v[0:15], v[120:123], v[52:55], v[0:15]
	s_setprio 1
	v_add_f32_e32 v79, v79, v234
	v_add_f32_e32 v64, v64, v65
	v_add_f32_e32 v66, v66, v67
	v_add_f32_e32 v68, v68, v69
	v_add_f32_e32 v70, v70, v71
	s_waitcnt lgkmcnt(13)
	v_mfma_f32_32x32x16_bf16 v[16:31], v[112:115], v[56:59], v[16:31]
	v_add_f32_e32 v72, v72, v73
	v_add_f32_e32 v74, v74, v75
	v_add_f32_e32 v76, v76, v77
	v_add_f32_e32 v78, v78, v79
	s_waitcnt lgkmcnt(11)
	v_mfma_f32_32x32x16_bf16 v[0:15], v[124:127], v[56:59], v[0:15]
	v_add_f32_e32 v64, v64, v66
	v_add_f32_e32 v68, v68, v70
	v_add_f32_e32 v72, v72, v74
	v_add_f32_e32 v76, v76, v78
	v_mfma_f32_32x32x16_bf16 v[16:31], v[108:111], v[60:63], v[16:31]
	v_add_f32_e32 v64, v64, v68
	v_add_f32_e32 v72, v72, v76
	v_add_f32_e32 v64, v64, v72
	v_add_f32_e32 v194, v194, v64
	s_waitcnt lgkmcnt(10)
	v_mfma_f32_32x32x16_bf16 v[0:15], v[100:103], v[60:63], v[0:15]
	s_cbranch_scc1 .LBB0_340
	s_mov_b32 s33, s77
	s_mov_b32 s77, s8
	s_branch .LBB0_336

.Lstg_x_11:
	v_exp_f32_e32 v56, v56
	v_exp_f32_e32 v57, v57
	v_exp_f32_e32 v58, v58
	v_exp_f32_e32 v59, v59
	v_exp_f32_e32 v219, v60
	v_exp_f32_e32 v220, v61
	v_exp_f32_e32 v221, v62
	v_exp_f32_e32 v222, v63
	v_cvt_pk_bf16_f32 v224, v64, v65
	v_cvt_pk_bf16_f32 v225, v66, v67
	v_cvt_pk_bf16_f32 v226, v68, v69
	v_cvt_pk_bf16_f32 v227, v70, v71
	v_cvt_pk_bf16_f32 v228, v72, v73
	v_cvt_pk_bf16_f32 v229, v74, v75
	v_cvt_pk_bf16_f32 v230, v76, v77
	v_cvt_pk_bf16_f32 v231, v78, v79
	v_cvt_pk_bf16_f32 v232, v48, v49
	v_cvt_pk_bf16_f32 v233, v50, v51
	v_cvt_pk_bf16_f32 v234, v52, v53
	v_cvt_pk_bf16_f32 v235, v54, v55
	v_cvt_pk_bf16_f32 v236, v56, v57
	v_cvt_pk_bf16_f32 v237, v58, v59
	v_cvt_pk_bf16_f32 v238, v219, v220
	v_cvt_pk_bf16_f32 v239, v221, v222
	s_setprio 2
	s_cmp_lg_u32 s98, 0
	s_cbranch_scc1 .Lstg_y_12
	s_setprio 1
	s_waitcnt lgkmcnt(0)
	s_barrier
.Lstg_y_12:
	s_mul_i32 s8, s45, 0x3400
	v_add_u32_e32 v189, s8, v208
	ds_read_b128 v[60:63], v189
	ds_read_b128 v[156:159], v189 offset:32
	ds_read_b128 v[164:167], v189 offset:6656
	ds_read_b128 v[152:155], v189 offset:64
	ds_read_b128 v[160:163], v189 offset:6688
	ds_read_b128 v[148:151], v189 offset:6720
	s_waitcnt lgkmcnt(13)
	v_mfma_f32_32x32x16_bf16 v[16:31], v[140:143], v[224:227], v[16:31]
	v_add_f32_e32 v64, v64, v48
	v_add_f32_e32 v65, v65, v49
	v_add_f32_e32 v66, v66, v50
	v_add_f32_e32 v67, v67, v51
	s_mul_i32 s44, s43, 0x3400
	s_add_i32 s18, s44, 0
	s_waitcnt lgkmcnt(11)
	v_mfma_f32_32x32x16_bf16 v[0:15], v[144:147], v[224:227], v[0:15]
	v_add_f32_e32 v68, v68, v52
	v_add_f32_e32 v69, v69, v53
	v_add_f32_e32 v70, v70, v54
	v_add_f32_e32 v71, v71, v55
	v_mfma_f32_32x32x16_bf16 v[16:31], v[128:131], v[228:231], v[16:31]
	v_add_f32_e32 v72, v72, v56
	v_add_f32_e32 v73, v73, v57
	v_add_f32_e32 v74, v74, v58
	v_add_f32_e32 v75, v75, v59
	s_waitcnt lgkmcnt(10)
	v_mfma_f32_32x32x16_bf16 v[0:15], v[132:135], v[228:231], v[0:15]
	s_setprio 1
	v_add_f32_e32 v76, v76, v219
	v_add_f32_e32 v77, v77, v220
	v_add_f32_e32 v78, v78, v221
	v_add_f32_e32 v79, v79, v222
	s_waitcnt lgkmcnt(9)
	v_mfma_f32_32x32x16_bf16 v[16:31], v[124:127], v[232:235], v[16:31]
	v_add_f32_e32 v64, v64, v65
	v_add_f32_e32 v66, v66, v67
	v_add_f32_e32 v68, v68, v69
	v_add_f32_e32 v70, v70, v71
	s_waitcnt lgkmcnt(7)
	v_mfma_f32_32x32x16_bf16 v[0:15], v[136:139], v[232:235], v[0:15]
	v_add_f32_e32 v72, v72, v73
	v_add_f32_e32 v74, v74, v75
	v_add_f32_e32 v76, v76, v77
	v_add_f32_e32 v78, v78, v79
	v_mfma_f32_32x32x16_bf16 v[16:31], v[120:123], v[236:239], v[16:31]
	v_add_f32_e32 v64, v64, v66
	v_add_f32_e32 v68, v68, v70
	v_add_f32_e32 v72, v72, v74
	v_add_f32_e32 v76, v76, v78
	v_add_u32_e32 v120, s18, v207
	s_waitcnt vmcnt(1)
	ds_write_b128 v120, v[112:115]
	s_waitcnt lgkmcnt(7)
	v_mfma_f32_32x32x16_bf16 v[0:15], v[116:119], v[236:239], v[0:15]
	v_add_f32_e32 v64, v64, v68
	v_add_f32_e32 v72, v72, v76
	s_and_saveexec_b64 s[8:9], s[4:5]
	v_add_u32_e32 v112, s18, v206
	ds_write_b128 v112, v[104:107]
	s_or_b64 exec, exec, s[8:9]
	v_add_f32_e32 v64, v64, v72
	s_cmp_eq_u32 s72, 1
	s_cselect_b32 s8, 0, 0x2400
	v_add_f32_e32 v190, v190, v64
	v_add_u32_e32 v48, s8, v198
	v_add_u32_e32 v48, 0x9800, v48
	s_waitcnt vmcnt(0)
	ds_write2_b64 v48, v[108:109], v[110:111] offset0:128 offset1:130
	s_add_i32 s33, s33, 1
	v_lshl_add_u64 v[194:195], v[194:195], 0, s[36:37]
	s_cmp_eq_u32 s33, 31
	v_lshl_add_u64 v[196:197], v[196:197], 0, s[22:23]
	s_cbranch_scc1 .LBB0_369
	s_mov_b32 s8, s42
	s_mov_b32 s42, s45
	s_branch .LBB0_361
